# main GEMM unit header: vmcnt drain moved behind accumulator zeroing (compiler epilogue paths drain at the latch)
# speedup vs baseline: 1.0077x; 1.0077x over previous
.LBB0_363:
	s_or_b64 exec, exec, s[6:7]
.LBB0_364:
	s_waitcnt vmcnt(0)
.Lmain_latch_fast:
	s_and_b64 vcc, exec, s[4:5]
	s_mov_b32 s51, s14
	s_mov_b32 s31, s12
	s_mov_b64 s[10:11], s[18:19]
	s_mov_b64 s[20:21], s[16:17]
	s_cbranch_vccnz .LBB0_826

.LBB0_371:
	s_add_u32 s6, s20, 0x80080
	s_addc_u32 s7, s21, 0
	s_add_u32 s13, s10, 0x100
	v_mov_b32_e32 v0, 0
	s_addc_u32 s15, s11, 0
	s_mov_b32 s20, -2
	v_mov_b32_e32 v1, v0
	s_waitcnt lgkmcnt(0)
	v_mov_b32_e32 v2, v0
	v_mov_b32_e32 v3, v0
	v_mov_b32_e32 v4, v0
	v_mov_b32_e32 v5, v0
	v_mov_b32_e32 v6, v0
	v_mov_b32_e32 v7, v0
	v_mov_b32_e32 v16, v0
	v_mov_b32_e32 v17, v0
	v_mov_b32_e32 v18, v0
	v_mov_b32_e32 v19, v0
	v_mov_b32_e32 v20, v0
	v_mov_b32_e32 v21, v0
	v_mov_b32_e32 v22, v0
	v_mov_b32_e32 v23, v0
	v_mov_b32_e32 v34, v0
	v_mov_b32_e32 v35, v0
	v_mov_b32_e32 v36, v0
	v_mov_b32_e32 v37, v0
	v_mov_b32_e32 v38, v0
	v_mov_b32_e32 v39, v0
	v_mov_b32_e32 v40, v0
	v_mov_b32_e32 v41, v0
	v_mov_b32_e32 v50, v0
	v_mov_b32_e32 v51, v0
	v_mov_b32_e32 v52, v0
	v_mov_b32_e32 v53, v0
	v_mov_b32_e32 v54, v0
	v_mov_b32_e32 v55, v0
	v_mov_b32_e32 v56, v0
	v_mov_b32_e32 v57, v0
	v_mov_b32_e32 v8, v0
	v_mov_b32_e32 v9, v0
	v_mov_b32_e32 v10, v0
	v_mov_b32_e32 v11, v0
	v_mov_b32_e32 v12, v0
	v_mov_b32_e32 v13, v0
	v_mov_b32_e32 v14, v0
	v_mov_b32_e32 v15, v0
	v_mov_b32_e32 v24, v0
	v_mov_b32_e32 v25, v0
	v_mov_b32_e32 v26, v0
	v_mov_b32_e32 v27, v0
	v_mov_b32_e32 v28, v0
	v_mov_b32_e32 v29, v0
	v_mov_b32_e32 v30, v0
	v_mov_b32_e32 v31, v0
	v_mov_b32_e32 v42, v0
	v_mov_b32_e32 v43, v0
	v_mov_b32_e32 v44, v0
	v_mov_b32_e32 v45, v0
	v_mov_b32_e32 v46, v0
	v_mov_b32_e32 v47, v0
	v_mov_b32_e32 v48, v0
	v_mov_b32_e32 v49, v0
	v_mov_b32_e32 v58, v0
	v_mov_b32_e32 v59, v0
	v_mov_b32_e32 v60, v0
	v_mov_b32_e32 v61, v0
	v_mov_b32_e32 v62, v0
	v_mov_b32_e32 v63, v0
	v_mov_b32_e32 v64, v0
	v_mov_b32_e32 v65, v0
	v_mov_b32_e32 v66, v0
	v_mov_b32_e32 v67, v0
	v_mov_b32_e32 v68, v0
	v_mov_b32_e32 v69, v0
	v_mov_b32_e32 v70, v0
	v_mov_b32_e32 v71, v0
	v_mov_b32_e32 v72, v0
	v_mov_b32_e32 v73, v0
	v_mov_b32_e32 v82, v0
	v_mov_b32_e32 v83, v0
	v_mov_b32_e32 v84, v0
	v_mov_b32_e32 v85, v0
	v_mov_b32_e32 v86, v0
	v_mov_b32_e32 v87, v0
	v_mov_b32_e32 v88, v0
	v_mov_b32_e32 v89, v0
	v_mov_b32_e32 v98, v0
	v_mov_b32_e32 v99, v0
	v_mov_b32_e32 v100, v0
	v_mov_b32_e32 v101, v0
	v_mov_b32_e32 v102, v0
	v_mov_b32_e32 v103, v0
	v_mov_b32_e32 v104, v0
	v_mov_b32_e32 v105, v0
	v_mov_b32_e32 v114, v0
	v_mov_b32_e32 v115, v0
	v_mov_b32_e32 v116, v0
	v_mov_b32_e32 v117, v0
	v_mov_b32_e32 v118, v0
	v_mov_b32_e32 v119, v0
	v_mov_b32_e32 v120, v0
	v_mov_b32_e32 v121, v0
	v_mov_b32_e32 v74, v0
	v_mov_b32_e32 v75, v0
	v_mov_b32_e32 v76, v0
	v_mov_b32_e32 v77, v0
	v_mov_b32_e32 v78, v0
	v_mov_b32_e32 v79, v0
	v_mov_b32_e32 v80, v0
	v_mov_b32_e32 v81, v0
	v_mov_b32_e32 v90, v0
	v_mov_b32_e32 v91, v0
	v_mov_b32_e32 v92, v0
	v_mov_b32_e32 v93, v0
	v_mov_b32_e32 v94, v0
	v_mov_b32_e32 v95, v0
	v_mov_b32_e32 v96, v0
	v_mov_b32_e32 v97, v0
	v_mov_b32_e32 v106, v0
	v_mov_b32_e32 v107, v0
	v_mov_b32_e32 v108, v0
	v_mov_b32_e32 v109, v0
	v_mov_b32_e32 v110, v0
	v_mov_b32_e32 v111, v0
	v_mov_b32_e32 v112, v0
	v_mov_b32_e32 v113, v0
	v_mov_b32_e32 v122, v0
	v_mov_b32_e32 v123, v0
	v_mov_b32_e32 v124, v0
	v_mov_b32_e32 v125, v0
	v_mov_b32_e32 v126, v0
	v_mov_b32_e32 v127, v0
	v_mov_b32_e32 v128, v0
	v_mov_b32_e32 v129, v0
	s_waitcnt vmcnt(0)
